# norm1 XB write-back stores nt (residual stream is re-read five phases later)
# speedup vs baseline: 1.0052x; 1.0052x over previous
; #define LAS __attribute__((address_space(3)))
; __device__ __forceinline__ unsigned cvt_pk_bf16(float lo, float hi) { const f32x2 v = {lo, hi}; return __builtin_bit_cast(unsigned, __builtin_convertvector(v, bf16x2_t)); }
; __device__ __forceinline__ float bf_lo(unsigned u) { return __uint_as_float(u << 16); }
; __device__ __forceinline__ float bf_hi(unsigned u) { return __uint_as_float(u & 0xffff0000u); }
; __device__ __forceinline__ void norm_mod_phase(Frame& F, int L, const float* gvec, int sh_chunk, int nrows, const float* pg, const float* pg2, const float* xlat, const float* xctx) {
;     ...
;         if (h2) {
;             const LAS f32x4* gq = vq + 3 * (D / 4); u32x2* xw_ = (u32x2*)((bf16_t*)(F.ws + WS_XB) + (size_t)r * D) + lane;
; #pragma unroll
;             for (int j = 0; j < 8; ++j) { const u32x2 yy = aux[1][j]; const f32x4 y4 = {bf_lo(yy.x), bf_hi(yy.x), bf_lo(yy.y), bf_hi(yy.y)}; v[j] += gq[64 * j] * y4; u32x2 w; w.x = cvt_pk_bf16(v[j].x, v[j].y); w.y = cvt_pk_bf16(v[j].z, v[j].w); xw_[64 * j] = w; }
;         }
.LBB0_226:
	s_and_b64 vcc, exec, s[40:41]
	v_lshlrev_b32_e32 v194, 16, v130
	v_and_b32_e32 v195, 0xffff0000, v130
	v_lshlrev_b32_e32 v192, 16, v131
	v_and_b32_e32 v193, 0xffff0000, v131
	v_lshlrev_b32_e32 v188, 16, v134
	v_and_b32_e32 v189, 0xffff0000, v134
	v_lshlrev_b32_e32 v190, 16, v135
	v_and_b32_e32 v191, 0xffff0000, v135
	v_lshlrev_b32_e32 v174, 16, v136
	v_and_b32_e32 v175, 0xffff0000, v136
	v_lshlrev_b32_e32 v172, 16, v137
	v_and_b32_e32 v173, 0xffff0000, v137
	v_lshlrev_b32_e32 v168, 16, v138
	v_and_b32_e32 v169, 0xffff0000, v138
	v_lshlrev_b32_e32 v170, 16, v139
	v_and_b32_e32 v171, 0xffff0000, v139
	v_lshlrev_b32_e32 v158, 16, v140
	v_and_b32_e32 v159, 0xffff0000, v140
	v_lshlrev_b32_e32 v156, 16, v141
	v_and_b32_e32 v157, 0xffff0000, v141
	v_lshlrev_b32_e32 v152, 16, v94
	v_and_b32_e32 v153, 0xffff0000, v94
	v_lshlrev_b32_e32 v154, 16, v95
	v_and_b32_e32 v155, 0xffff0000, v95
	v_lshlrev_b32_e32 v28, 16, v112
	v_and_b32_e32 v29, 0xffff0000, v112
	v_lshlrev_b32_e32 v24, 16, v113
	v_and_b32_e32 v25, 0xffff0000, v113
	v_lshlrev_b32_e32 v16, 16, v114
	v_and_b32_e32 v17, 0xffff0000, v114
	v_lshlrev_b32_e32 v20, 16, v115
	v_and_b32_e32 v21, 0xffff0000, v115
	s_cbranch_vccnz .LBB0_228
	ds_read_b128 v[198:201], v196 offset:24576
	s_ashr_i32 s11, s10, 31
	s_lshl_b64 s[4:5], s[10:11], 12
	v_lshl_add_u64 v[150:151], v[74:75], 0, s[4:5]
	s_waitcnt lgkmcnt(0)
	v_pk_fma_f32 v[34:35], v[200:201], v[192:193], v[34:35]
	v_pk_fma_f32 v[32:33], v[198:199], v[194:195], v[32:33]
	v_cvt_pk_bf16_f32 v199, v34, v35
	v_cvt_pk_bf16_f32 v198, v32, v33
	global_store_dwordx2 v[150:151], v[198:199], off nt
	ds_read_b128 v[198:201], v196 offset:25600
	s_waitcnt lgkmcnt(0)
	v_pk_fma_f32 v[38:39], v[200:201], v[190:191], v[38:39]
	v_pk_fma_f32 v[36:37], v[198:199], v[188:189], v[36:37]
	v_cvt_pk_bf16_f32 v199, v38, v39
	v_cvt_pk_bf16_f32 v198, v36, v37
	global_store_dwordx2 v[150:151], v[198:199], off offset:512 nt
	ds_read_b128 v[198:201], v196 offset:26624
	s_waitcnt lgkmcnt(0)
	v_pk_fma_f32 v[42:43], v[200:201], v[172:173], v[42:43]
	v_pk_fma_f32 v[40:41], v[198:199], v[174:175], v[40:41]
	v_cvt_pk_bf16_f32 v199, v42, v43
	v_cvt_pk_bf16_f32 v198, v40, v41
	global_store_dwordx2 v[150:151], v[198:199], off offset:1024 nt
	ds_read_b128 v[198:201], v196 offset:27648
	s_waitcnt lgkmcnt(0)
	v_pk_fma_f32 v[46:47], v[200:201], v[170:171], v[46:47]
	v_pk_fma_f32 v[44:45], v[198:199], v[168:169], v[44:45]
	v_cvt_pk_bf16_f32 v199, v46, v47
	v_cvt_pk_bf16_f32 v198, v44, v45
	global_store_dwordx2 v[150:151], v[198:199], off offset:1536 nt
	ds_read_b128 v[198:201], v196 offset:28672
	s_waitcnt lgkmcnt(0)
	v_pk_fma_f32 v[50:51], v[200:201], v[156:157], v[50:51]
	v_pk_fma_f32 v[48:49], v[198:199], v[158:159], v[48:49]
	v_cvt_pk_bf16_f32 v199, v50, v51
	v_cvt_pk_bf16_f32 v198, v48, v49
	global_store_dwordx2 v[150:151], v[198:199], off offset:2048 nt
	ds_read_b128 v[198:201], v196 offset:29696
	s_waitcnt lgkmcnt(0)
	v_pk_fma_f32 v[54:55], v[200:201], v[154:155], v[54:55]
	v_pk_fma_f32 v[52:53], v[198:199], v[152:153], v[52:53]
	v_cvt_pk_bf16_f32 v199, v54, v55
	v_cvt_pk_bf16_f32 v198, v52, v53
	global_store_dwordx2 v[150:151], v[198:199], off offset:2560 nt
	ds_read_b128 v[198:201], v196 offset:30720
	s_waitcnt lgkmcnt(0)
	v_pk_fma_f32 v[58:59], v[200:201], v[24:25], v[58:59]
	v_pk_fma_f32 v[56:57], v[198:199], v[28:29], v[56:57]
	v_cvt_pk_bf16_f32 v199, v58, v59
	v_cvt_pk_bf16_f32 v198, v56, v57
	global_store_dwordx2 v[150:151], v[198:199], off offset:3072 nt
	ds_read_b128 v[198:201], v196 offset:31744
	s_waitcnt lgkmcnt(0)
	v_pk_fma_f32 v[62:63], v[200:201], v[20:21], v[62:63]
	v_pk_fma_f32 v[60:61], v[198:199], v[16:17], v[60:61]
	v_cvt_pk_bf16_f32 v199, v62, v63
	v_cvt_pk_bf16_f32 v198, v60, v61
	global_store_dwordx2 v[150:151], v[198:199], off offset:3584 nt
